# phase-0 context copy: both trips' loads in flight before the stores (G=256 path), on top of v31
# speedup vs baseline: 1.0031x; 1.0031x over previous
; __device__ __forceinline__ void p0_phase(ArgP a, LAS unsigned char* lds, int tid, int wave, int lane, int bid, int G) {
;     ...
;     { const f32x4* xs = (const f32x4*)a->in[0]; f32x4* xd = (f32x4*)a->out;
;       for (int i = gt; i < MLAT * D / 4; i += GT) xd[i] = xs[i];
;       const f32x4* cs = (const f32x4*)a->in[2]; f32x4* cd = (f32x4*)(a->ws + OFF_HC);
;       for (int i = gt; i < NB * C * D / 4; i += GT) cd[i] = cs[i]; }
.LBB0_1095:
	s_mov_b32 s1, 0x40000
	v_cmp_gt_i32_e32 vcc, s1, v6
	s_and_saveexec_b64 s[2:3], vcc
	s_cbranch_execz .LBB0_1098
	v_ashrrev_i32_e32 v7, 31, v6
	s_ashr_i32 s1, s0, 31
	v_lshlrev_b64 v[8:9], 4, v[6:7]
	s_lshl_b64 s[8:9], s[0:1], 4
	s_cmpk_lg_i32 s90, 0x100
	s_cbranch_scc1 .Lctx_generic
	s_load_dwordx2 s[14:15], s[30:31], 0x10
	v_lshl_add_u64 v[14:15], s[36:37], 0, v[8:9]
	s_waitcnt lgkmcnt(0)
	v_lshl_add_u64 v[10:11], s[14:15], 0, v[8:9]
	global_load_dwordx4 v[16:19], v[10:11], off
	v_lshl_add_u64 v[10:11], v[10:11], 0, s[8:9]
	v_lshl_add_u64 v[20:21], v[14:15], 0, s[8:9]
	global_load_dwordx4 v[10:13], v[10:11], off
	s_waitcnt vmcnt(1)
	global_store_dwordx4 v[14:15], v[16:19], off
	s_waitcnt vmcnt(1)
	global_store_dwordx4 v[20:21], v[10:13], off
	s_branch .LBB0_1098
.Lctx_generic:
	s_mov_b64 s[12:13], 0
.LBB0_1097:
	s_load_dwordx2 s[14:15], s[30:31], 0x10
	v_add_u32_e32 v6, s0, v6
	s_mov_b32 s1, 0x3ffff
	v_cmp_lt_i32_e32 vcc, s1, v6
	v_lshl_add_u64 v[14:15], s[36:37], 0, v[8:9]
	s_waitcnt lgkmcnt(0)
	v_lshl_add_u64 v[10:11], s[14:15], 0, v[8:9]
	global_load_dwordx4 v[10:13], v[10:11], off
	v_lshl_add_u64 v[8:9], v[8:9], 0, s[8:9]
	s_or_b64 s[12:13], vcc, s[12:13]
	s_waitcnt vmcnt(0)
	global_store_dwordx4 v[14:15], v[10:13], off
	s_andn2_b64 exec, exec, s[12:13]
	s_cbranch_execnz .LBB0_1097
